# v2 plus: phase_pb loop 8 loads in flight, prep_x row loops 4 loads in flight with counted vmcnt
# speedup vs baseline: 1.0054x; 1.0054x over previous
; DI unsigned pk2(float lo, float hi) { typedef float f2 __attribute__((ext_vector_type(2))); typedef __bf16 b2 __attribute__((ext_vector_type(2))); f2 v = {lo, hi}; b2 b = __builtin_convertvector(v, b2); return __builtin_bit_cast(unsigned, b); }
; DI void phase_prep_x(const float* x, bf16_t* xb, float* rsq, int M, int gw, int NGW, int lane) {
;     for (int m = gw; m < M; m += NGW) {
;         const f32x4* xr = (const f32x4*)(x + (size_t)m * DM) + lane; u32x2* o = (u32x2*)(xb + (size_t)m * DM) + lane; float s = 0.f;
; #pragma unroll
;         for (int j = 0; j < 4; ++j) { const f32x4 v = xr[64 * j]; s += (v.x * v.x + v.y * v.y) + (v.z * v.z + v.w * v.w); u32x2 w; w.x = pk2(v.x, v.y); w.y = pk2(v.z, v.w); o[64 * j] = w; }
;         s = wave_sum(s);
;         if (lane < 16) rsq[(size_t)m * 16 + lane] = (lane == 0) ? s : 0.f;
;     }
.LBB0_11:
	s_waitcnt lgkmcnt(0)
	global_load_dwordx4 v[16:19], v[6:7], off offset:-3072
	global_load_dwordx4 v[20:23], v[6:7], off offset:-2048
	global_load_dwordx4 v[24:27], v[6:7], off offset:-1024
	global_load_dwordx4 v[28:31], v[6:7], off
	v_lshl_add_u64 v[34:35], s[0:1], 0, v[4:5]
	v_add_co_u32_e32 v32, vcc, s3, v34
	s_nop 1
	v_addc_co_u32_e32 v33, vcc, 0, v35, vcc
	s_waitcnt vmcnt(3)
	v_cvt_pk_bf16_f32 v36, v16, v17
	v_cvt_pk_bf16_f32 v37, v18, v19
	global_store_dwordx2 v[32:33], v[36:37], off
	v_mul_f32_e32 v15, v17, v17
	v_mul_f32_e32 v17, v19, v19
	v_fmac_f32_e32 v15, v16, v16
	v_fmac_f32_e32 v17, v18, v18
	v_add_f32_e32 v15, v15, v17
	s_waitcnt vmcnt(3)
	v_cvt_pk_bf16_f32 v38, v20, v21
	v_cvt_pk_bf16_f32 v39, v22, v23
	global_store_dwordx2 v[32:33], v[38:39], off offset:512
	v_mul_f32_e32 v16, v21, v21
	v_mul_f32_e32 v17, v23, v23
	v_fmac_f32_e32 v16, v20, v20
	v_fmac_f32_e32 v17, v22, v22
	v_add_f32_e32 v16, v16, v17
	v_add_f32_e32 v15, v15, v16
	s_waitcnt vmcnt(3)
	v_cvt_pk_bf16_f32 v40, v24, v25
	v_cvt_pk_bf16_f32 v41, v26, v27
	global_store_dwordx2 v[32:33], v[40:41], off offset:1024
	v_mul_f32_e32 v16, v25, v25
	v_mul_f32_e32 v17, v27, v27
	v_fmac_f32_e32 v16, v24, v24
	v_fmac_f32_e32 v17, v26, v26
	v_add_f32_e32 v16, v16, v17
	v_add_f32_e32 v15, v15, v16
	s_waitcnt vmcnt(3)
	v_mul_f32_e32 v16, v29, v29
	v_mul_f32_e32 v17, v31, v31
	v_fmac_f32_e32 v16, v28, v28
	v_fmac_f32_e32 v17, v30, v30
	v_add_f32_e32 v16, v16, v17
	v_add_f32_e32 v15, v15, v16
	ds_bpermute_b32 v16, v9, v15
	v_cvt_pk_bf16_f32 v18, v28, v29
	v_cvt_pk_bf16_f32 v19, v30, v31
	global_store_dwordx2 v[32:33], v[18:19], off offset:1536
	s_waitcnt lgkmcnt(0)
	v_add_f32_e32 v15, v15, v16
	ds_bpermute_b32 v16, v10, v15
	s_waitcnt lgkmcnt(0)
	v_add_f32_e32 v15, v15, v16
	ds_bpermute_b32 v16, v11, v15
	s_waitcnt lgkmcnt(0)
	v_add_f32_e32 v15, v15, v16
	ds_bpermute_b32 v16, v12, v15
	s_waitcnt lgkmcnt(0)
	v_add_f32_e32 v15, v15, v16
	ds_bpermute_b32 v16, v13, v15
	s_waitcnt lgkmcnt(0)
	v_add_f32_e32 v15, v15, v16
	ds_bpermute_b32 v16, v14, v15
	s_and_saveexec_b64 s[14:15], s[4:5]
	s_cbranch_execz .LBB0_10
	s_waitcnt lgkmcnt(0)
	v_add_f32_e32 v15, v15, v16
	v_cndmask_b32_e64 v15, 0, v15, s[6:7]
	v_lshl_add_u64 v[16:17], s[0:1], 0, v[2:3]
	global_store_dword v[16:17], v15, off
	s_branch .LBB0_10

; DI unsigned pk2(float lo, float hi) { typedef float f2 __attribute__((ext_vector_type(2))); typedef __bf16 b2 __attribute__((ext_vector_type(2))); f2 v = {lo, hi}; b2 b = __builtin_convertvector(v, b2); return __builtin_bit_cast(unsigned, b); }
; DI void phase_pb(const Params& p, const Grp& G, int layer, int g, int gw, int NGW, int lane) {
;     bf16_t* pb = (bf16_t*)(p.ws + OFF_PB); const float* pin = (g ? p.p_in[1] : p.p_in[0]) + (size_t)layer * G.M * PLE;
;     for (int m = gw; m < G.M; m += NGW) { const f32x4 v = *((const f32x4*)(pin + (size_t)m * PLE) + lane); u32x2 w; w.x = pk2(v.x, v.y); w.y = pk2(v.z, v.w); *((u32x2*)(pb + (size_t)m * PLE) + lane) = w; }
; }
.LBB0_439:
	global_load_dwordx4 v[4:7], v[0:1], off
	v_lshl_add_u64 v[0:1], v[0:1], 0, s[6:7]
	global_load_dwordx4 v[8:11], v[0:1], off
	v_lshl_add_u64 v[0:1], v[0:1], 0, s[6:7]
	global_load_dwordx4 v[12:15], v[0:1], off
	v_lshl_add_u64 v[0:1], v[0:1], 0, s[6:7]
	global_load_dwordx4 v[16:19], v[0:1], off
	v_lshl_add_u64 v[0:1], v[0:1], 0, s[6:7]
	global_load_dwordx4 v[20:23], v[0:1], off
	v_lshl_add_u64 v[0:1], v[0:1], 0, s[6:7]
	global_load_dwordx4 v[24:27], v[0:1], off
	v_lshl_add_u64 v[0:1], v[0:1], 0, s[6:7]
	global_load_dwordx4 v[28:31], v[0:1], off
	v_lshl_add_u64 v[0:1], v[0:1], 0, s[6:7]
	global_load_dwordx4 v[32:35], v[0:1], off
	v_lshl_add_u64 v[0:1], v[0:1], 0, s[6:7]
	s_lshl_b32 s99, s72, 3
	s_add_i32 s0, s0, s99
	s_cmp_ge_i32 s0, s73
	s_waitcnt vmcnt(7)
	v_cvt_pk_bf16_f32 v4, v4, v5
	v_cvt_pk_bf16_f32 v5, v6, v7
	global_store_dwordx2 v[2:3], v[4:5], off
	v_lshl_add_u64 v[2:3], v[2:3], 0, s[8:9]
	s_waitcnt vmcnt(7)
	v_cvt_pk_bf16_f32 v8, v8, v9
	v_cvt_pk_bf16_f32 v9, v10, v11
	global_store_dwordx2 v[2:3], v[8:9], off
	v_lshl_add_u64 v[2:3], v[2:3], 0, s[8:9]
	s_waitcnt vmcnt(7)
	v_cvt_pk_bf16_f32 v12, v12, v13
	v_cvt_pk_bf16_f32 v13, v14, v15
	global_store_dwordx2 v[2:3], v[12:13], off
	v_lshl_add_u64 v[2:3], v[2:3], 0, s[8:9]
	s_waitcnt vmcnt(7)
	v_cvt_pk_bf16_f32 v16, v16, v17
	v_cvt_pk_bf16_f32 v17, v18, v19
	global_store_dwordx2 v[2:3], v[16:17], off
	v_lshl_add_u64 v[2:3], v[2:3], 0, s[8:9]
	s_waitcnt vmcnt(7)
	v_cvt_pk_bf16_f32 v20, v20, v21
	v_cvt_pk_bf16_f32 v21, v22, v23
	global_store_dwordx2 v[2:3], v[20:21], off
	v_lshl_add_u64 v[2:3], v[2:3], 0, s[8:9]
	s_waitcnt vmcnt(7)
	v_cvt_pk_bf16_f32 v24, v24, v25
	v_cvt_pk_bf16_f32 v25, v26, v27
	global_store_dwordx2 v[2:3], v[24:25], off
	v_lshl_add_u64 v[2:3], v[2:3], 0, s[8:9]
	s_waitcnt vmcnt(7)
	v_cvt_pk_bf16_f32 v28, v28, v29
	v_cvt_pk_bf16_f32 v29, v30, v31
	global_store_dwordx2 v[2:3], v[28:29], off
	v_lshl_add_u64 v[2:3], v[2:3], 0, s[8:9]
	s_waitcnt vmcnt(7)
	v_cvt_pk_bf16_f32 v32, v32, v33
	v_cvt_pk_bf16_f32 v33, v34, v35
	global_store_dwordx2 v[2:3], v[32:33], off
	v_lshl_add_u64 v[2:3], v[2:3], 0, s[8:9]
	s_cbranch_scc0 .LBB0_439

; DI unsigned pk2(float lo, float hi) { typedef float f2 __attribute__((ext_vector_type(2))); typedef __bf16 b2 __attribute__((ext_vector_type(2))); f2 v = {lo, hi}; b2 b = __builtin_convertvector(v, b2); return __builtin_bit_cast(unsigned, b); }
; DI void phase_prep_x(const float* x, bf16_t* xb, float* rsq, int M, int gw, int NGW, int lane) {
;     for (int m = gw; m < M; m += NGW) {
;         const f32x4* xr = (const f32x4*)(x + (size_t)m * DM) + lane; u32x2* o = (u32x2*)(xb + (size_t)m * DM) + lane; float s = 0.f;
; #pragma unroll
;         for (int j = 0; j < 4; ++j) { const f32x4 v = xr[64 * j]; s += (v.x * v.x + v.y * v.y) + (v.z * v.z + v.w * v.w); u32x2 w; w.x = pk2(v.x, v.y); w.y = pk2(v.z, v.w); o[64 * j] = w; }
;         s = wave_sum(s);
;         if (lane < 16) rsq[(size_t)m * 16 + lane] = (lane == 0) ? s : 0.f;
;     }
.LBB0_600:
	s_waitcnt lgkmcnt(0)
	global_load_dwordx4 v[12:15], v[4:5], off offset:-3072
	global_load_dwordx4 v[16:19], v[4:5], off offset:-2048
	global_load_dwordx4 v[20:23], v[4:5], off offset:-1024
	global_load_dwordx4 v[24:27], v[4:5], off
	v_lshl_add_u64 v[30:31], s[62:63], 0, v[2:3]
	s_mov_b32 s0, 0x6e00000
	v_add_co_u32_e32 v28, vcc, s0, v30
	s_nop 1
	v_addc_co_u32_e32 v29, vcc, 0, v31, vcc
	s_waitcnt vmcnt(3)
	v_cvt_pk_bf16_f32 v32, v12, v13
	v_cvt_pk_bf16_f32 v33, v14, v15
	global_store_dwordx2 v[28:29], v[32:33], off
	v_mul_f32_e32 v13, v13, v13
	v_mul_f32_e32 v15, v15, v15
	v_fmac_f32_e32 v13, v12, v12
	v_fmac_f32_e32 v15, v14, v14
	v_add_f32_e32 v12, v13, v15
	s_waitcnt vmcnt(3)
	v_cvt_pk_bf16_f32 v34, v16, v17
	v_cvt_pk_bf16_f32 v35, v18, v19
	global_store_dwordx2 v[28:29], v[34:35], off offset:512
	v_mul_f32_e32 v13, v17, v17
	v_mul_f32_e32 v14, v19, v19
	v_fmac_f32_e32 v13, v16, v16
	v_fmac_f32_e32 v14, v18, v18
	v_add_f32_e32 v13, v13, v14
	v_add_f32_e32 v12, v12, v13
	s_waitcnt vmcnt(3)
	v_cvt_pk_bf16_f32 v36, v20, v21
	v_cvt_pk_bf16_f32 v37, v22, v23
	global_store_dwordx2 v[28:29], v[36:37], off offset:1024
	v_mul_f32_e32 v13, v21, v21
	v_mul_f32_e32 v14, v23, v23
	v_fmac_f32_e32 v13, v20, v20
	v_fmac_f32_e32 v14, v22, v22
	v_add_f32_e32 v13, v13, v14
	v_add_f32_e32 v12, v12, v13
	s_waitcnt vmcnt(3)
	v_mul_f32_e32 v13, v25, v25
	v_mul_f32_e32 v14, v27, v27
	v_fmac_f32_e32 v13, v24, v24
	v_fmac_f32_e32 v14, v26, v26
	v_add_f32_e32 v13, v13, v14
	v_add_f32_e32 v12, v12, v13
	ds_bpermute_b32 v13, v6, v12
	v_cvt_pk_bf16_f32 v14, v24, v25
	v_cvt_pk_bf16_f32 v15, v26, v27
	global_store_dwordx2 v[28:29], v[14:15], off offset:1536
	s_waitcnt lgkmcnt(0)
	v_add_f32_e32 v12, v12, v13
	ds_bpermute_b32 v13, v7, v12
	s_waitcnt lgkmcnt(0)
	v_add_f32_e32 v12, v12, v13
	ds_bpermute_b32 v13, v8, v12
	s_waitcnt lgkmcnt(0)
	v_add_f32_e32 v12, v12, v13
	ds_bpermute_b32 v13, v9, v12
	s_waitcnt lgkmcnt(0)
	v_add_f32_e32 v12, v12, v13
	ds_bpermute_b32 v13, v10, v12
	s_waitcnt lgkmcnt(0)
	v_add_f32_e32 v12, v12, v13
	ds_bpermute_b32 v13, v11, v12
	s_and_saveexec_b64 s[0:1], s[38:39]
	s_cbranch_execz .LBB0_599
	s_waitcnt lgkmcnt(0)
	v_add_f32_e32 v12, v12, v13
	v_cndmask_b32_e64 v14, 0, v12, s[40:41]
	v_lshl_add_u64 v[12:13], s[62:63], 0, v[0:1]
	global_store_dword v[12:13], v14, off
	s_branch .LBB0_599
